# P8 residual epilogue: 11 base loads in flight with counted vmcnt instead of load-wait-store chain
# baseline (speedup 1.0000x reference)
;     __device__ __forceinline__ void operator()(const f32x4 (&acc)[2][2][4][2], const Unit& u, int wr, int wc, int fr, int fq) const {
;         const int row0 = u.pm * BM + wr * 64 + fr, col0 = u.pn * BM + wc * 32 + 4 * fq, b = (u.pm * BM) >> 12;
;         f32x4 gv[2][2];
; #pragma unroll
;         for (int bj = 0; bj < 2; ++bj)
; #pragma unroll
;             for (int n = 0; n < 2; ++n) gv[bj][n] = *(const f32x4*)(gate + (size_t)b * 12288 + col0 + bj * HALF + n * 16);
; #pragma unroll
;         for (int ai = 0; ai < 2; ++ai)
; #pragma unroll
;             for (int m = 0; m < 4; ++m) { const size_t off = (size_t)(row0 + ai * HALF + m * 16) * 2048 + col0;
; #pragma unroll
;                 for (int bj = 0; bj < 2; ++bj)
; #pragma unroll
;                     for (int n = 0; n < 2; ++n) { const f32x4 bs = __builtin_nontemporal_load((const f32x4*)(base + off + bj * HALF + n * 16));
;                         *(f32x4*)(out + off + bj * HALF + n * 16) = bs + gv[bj][n] * acc[ai][bj][m][n]; } }
;     }
.LBB0_1074:
	s_ashr_i32 s17, s24, 4
	v_lshl_add_u32 v160, s24, 8, v162
	v_lshl_or_b32 v64, s25, 8, v164
	s_mul_hi_i32 s19, s17, 0xc000
	s_mul_i32 s17, s17, 0xc000
	v_ashrrev_i32_e32 v161, 31, v160
	s_add_u32 s26, s40, s17
	v_ashrrev_i32_e32 v65, 31, v64
	v_lshlrev_b64 v[156:157], 13, v[160:161]
	s_addc_u32 s27, s41, s19
	v_lshlrev_b64 v[158:159], 2, v[64:65]
	v_lshl_add_u64 v[156:157], s[66:67], 0, v[156:157]
	v_lshl_add_u64 v[64:65], s[26:27], 0, v[158:159]
	v_lshl_add_u64 v[156:157], v[156:157], 0, v[158:159]
	global_load_dwordx4 v[128:131], v[64:65], off
	global_load_dwordx4 v[116:119], v[64:65], off offset:64
	global_load_dwordx4 v[108:111], v[64:65], off offset:512
	s_nop 0
	global_load_dwordx4 v[64:67], v[64:65], off offset:576
	s_mov_b64 s[24:25], -1
	s_mov_b64 s[98:99], 0x20000
	s_mov_b64 s[100:101], 0xa0000
	v_mov_b64_e32 v[158:159], v[156:157]
	global_load_dwordx4 v[168:171], v[158:159], off nt
	global_load_dwordx4 v[172:175], v[158:159], off offset:64 nt
	global_load_dwordx4 v[176:179], v[158:159], off offset:512 nt
	global_load_dwordx4 v[180:183], v[158:159], off offset:576 nt
	v_lshl_add_u64 v[158:159], v[158:159], 0, s[98:99]
	global_load_dwordx4 v[184:187], v[158:159], off nt
	global_load_dwordx4 v[188:191], v[158:159], off offset:64 nt
	global_load_dwordx4 v[192:195], v[158:159], off offset:512 nt
	global_load_dwordx4 v[196:199], v[158:159], off offset:576 nt
	v_lshl_add_u64 v[158:159], v[158:159], 0, s[98:99]
	global_load_dwordx4 v[200:203], v[158:159], off nt
	global_load_dwordx4 v[204:207], v[158:159], off offset:64 nt
	global_load_dwordx4 v[208:211], v[158:159], off offset:512 nt
	s_waitcnt vmcnt(10)
	v_pk_fma_f32 v[142:143], v[142:143], v[130:131], v[170:171]
	v_pk_fma_f32 v[140:141], v[140:141], v[128:129], v[168:169]
	global_store_dwordx4 v[156:157], v[140:143], off
	global_load_dwordx4 v[168:171], v[158:159], off offset:576 nt
	v_lshl_add_u64 v[158:159], v[158:159], 0, s[98:99]
	s_waitcnt vmcnt(11)
	v_pk_fma_f32 v[138:139], v[138:139], v[118:119], v[174:175]
	v_pk_fma_f32 v[136:137], v[136:137], v[116:117], v[172:173]
	global_store_dwordx4 v[156:157], v[136:139], off offset:64
	global_load_dwordx4 v[172:175], v[158:159], off nt
	s_waitcnt vmcnt(12)
	v_pk_fma_f32 v[134:135], v[134:135], v[110:111], v[178:179]
	v_pk_fma_f32 v[132:133], v[132:133], v[108:109], v[176:177]
	global_store_dwordx4 v[156:157], v[132:135], off offset:512
	global_load_dwordx4 v[176:179], v[158:159], off offset:64 nt
	s_waitcnt vmcnt(13)
	v_pk_fma_f32 v[126:127], v[126:127], v[66:67], v[182:183]
	v_pk_fma_f32 v[124:125], v[124:125], v[64:65], v[180:181]
	global_store_dwordx4 v[156:157], v[124:127], off offset:576
	v_lshl_add_u64 v[156:157], v[156:157], 0, s[98:99]
	global_load_dwordx4 v[180:183], v[158:159], off offset:512 nt
	s_waitcnt vmcnt(14)
	v_pk_fma_f32 v[122:123], v[122:123], v[130:131], v[186:187]
	v_pk_fma_f32 v[120:121], v[120:121], v[128:129], v[184:185]
	global_store_dwordx4 v[156:157], v[120:123], off
	global_load_dwordx4 v[184:187], v[158:159], off offset:576 nt
	v_lshl_add_u64 v[158:159], v[158:159], 0, s[100:101]
	s_waitcnt vmcnt(15)
	v_pk_fma_f32 v[114:115], v[114:115], v[118:119], v[190:191]
	v_pk_fma_f32 v[112:113], v[112:113], v[116:117], v[188:189]
	global_store_dwordx4 v[156:157], v[112:115], off offset:64
	global_load_dwordx4 v[188:191], v[158:159], off nt
	s_waitcnt vmcnt(16)
	v_pk_fma_f32 v[106:107], v[106:107], v[110:111], v[194:195]
	v_pk_fma_f32 v[104:105], v[104:105], v[108:109], v[192:193]
	global_store_dwordx4 v[156:157], v[104:107], off offset:512
	global_load_dwordx4 v[192:195], v[158:159], off offset:64 nt
	s_waitcnt vmcnt(17)
	v_pk_fma_f32 v[102:103], v[102:103], v[66:67], v[198:199]
	v_pk_fma_f32 v[100:101], v[100:101], v[64:65], v[196:197]
	global_store_dwordx4 v[156:157], v[100:103], off offset:576
	v_lshl_add_u64 v[156:157], v[156:157], 0, s[98:99]
	global_load_dwordx4 v[196:199], v[158:159], off offset:512 nt
	s_waitcnt vmcnt(18)
	v_pk_fma_f32 v[98:99], v[98:99], v[130:131], v[202:203]
	v_pk_fma_f32 v[96:97], v[96:97], v[128:129], v[200:201]
	global_store_dwordx4 v[156:157], v[96:99], off
	global_load_dwordx4 v[200:203], v[158:159], off offset:576 nt
	v_lshl_add_u64 v[158:159], v[158:159], 0, s[98:99]
	s_waitcnt vmcnt(19)
	v_pk_fma_f32 v[94:95], v[94:95], v[118:119], v[206:207]
	v_pk_fma_f32 v[92:93], v[92:93], v[116:117], v[204:205]
	global_store_dwordx4 v[156:157], v[92:95], off offset:64
	global_load_dwordx4 v[204:207], v[158:159], off nt
	s_waitcnt vmcnt(20)
	v_pk_fma_f32 v[90:91], v[90:91], v[110:111], v[210:211]
	v_pk_fma_f32 v[88:89], v[88:89], v[108:109], v[208:209]
	global_store_dwordx4 v[156:157], v[88:91], off offset:512
	global_load_dwordx4 v[208:211], v[158:159], off offset:64 nt
	s_waitcnt vmcnt(20)
	v_pk_fma_f32 v[86:87], v[86:87], v[66:67], v[170:171]
	v_pk_fma_f32 v[84:85], v[84:85], v[64:65], v[168:169]
	global_store_dwordx4 v[156:157], v[84:87], off offset:576
	v_lshl_add_u64 v[156:157], v[156:157], 0, s[98:99]
	global_load_dwordx4 v[168:171], v[158:159], off offset:512 nt
	s_waitcnt vmcnt(20)
;     __device__ __forceinline__ void operator()(const f32x4 (&acc)[2][2][4][2], const Unit& u, int wr, int wc, int fr, int fq) const {
;     ...
;         for (int ai = 0; ai < 2; ++ai)
; #pragma unroll
;             for (int m = 0; m < 4; ++m) { const size_t off = (size_t)(row0 + ai * HALF + m * 16) * 2048 + col0;
; #pragma unroll
;                 for (int bj = 0; bj < 2; ++bj)
; #pragma unroll
;                     for (int n = 0; n < 2; ++n) { const f32x4 bs = __builtin_nontemporal_load((const f32x4*)(base + off + bj * HALF + n * 16));
;                         *(f32x4*)(out + off + bj * HALF + n * 16) = bs + gv[bj][n] * acc[ai][bj][m][n]; } }
;     }
	v_pk_fma_f32 v[82:83], v[82:83], v[130:131], v[174:175]
	v_pk_fma_f32 v[80:81], v[80:81], v[128:129], v[172:173]
	global_store_dwordx4 v[156:157], v[80:83], off
	global_load_dwordx4 v[172:175], v[158:159], off offset:576 nt
	v_lshl_add_u64 v[158:159], v[158:159], 0, s[98:99]
	s_waitcnt vmcnt(20)
	v_pk_fma_f32 v[78:79], v[78:79], v[118:119], v[178:179]
	v_pk_fma_f32 v[76:77], v[76:77], v[116:117], v[176:177]
	global_store_dwordx4 v[156:157], v[76:79], off offset:64
	global_load_dwordx4 v[176:179], v[158:159], off nt
	s_waitcnt vmcnt(20)
	v_pk_fma_f32 v[74:75], v[74:75], v[110:111], v[182:183]
	v_pk_fma_f32 v[72:73], v[72:73], v[108:109], v[180:181]
	global_store_dwordx4 v[156:157], v[72:75], off offset:512
	global_load_dwordx4 v[180:183], v[158:159], off offset:64 nt
	s_waitcnt vmcnt(20)
	v_pk_fma_f32 v[70:71], v[70:71], v[66:67], v[186:187]
	v_pk_fma_f32 v[68:69], v[68:69], v[64:65], v[184:185]
	global_store_dwordx4 v[156:157], v[68:71], off offset:576
	v_lshl_add_u64 v[156:157], v[156:157], 0, s[100:101]
	global_load_dwordx4 v[184:187], v[158:159], off offset:512 nt
	s_waitcnt vmcnt(20)
	v_pk_fma_f32 v[62:63], v[62:63], v[130:131], v[190:191]
	v_pk_fma_f32 v[60:61], v[60:61], v[128:129], v[188:189]
	global_store_dwordx4 v[156:157], v[60:63], off
	global_load_dwordx4 v[188:191], v[158:159], off offset:576 nt
	v_lshl_add_u64 v[158:159], v[158:159], 0, s[98:99]
	s_waitcnt vmcnt(20)
	v_pk_fma_f32 v[58:59], v[58:59], v[118:119], v[194:195]
	v_pk_fma_f32 v[56:57], v[56:57], v[116:117], v[192:193]
	global_store_dwordx4 v[156:157], v[56:59], off offset:64
	global_load_dwordx4 v[192:195], v[158:159], off nt
	s_waitcnt vmcnt(20)
	v_pk_fma_f32 v[54:55], v[54:55], v[110:111], v[198:199]
	v_pk_fma_f32 v[52:53], v[52:53], v[108:109], v[196:197]
	global_store_dwordx4 v[156:157], v[52:55], off offset:512
	global_load_dwordx4 v[196:199], v[158:159], off offset:64 nt
	s_waitcnt vmcnt(20)
	v_pk_fma_f32 v[50:51], v[50:51], v[66:67], v[202:203]
	v_pk_fma_f32 v[48:49], v[48:49], v[64:65], v[200:201]
	global_store_dwordx4 v[156:157], v[48:51], off offset:576
	v_lshl_add_u64 v[156:157], v[156:157], 0, s[98:99]
	global_load_dwordx4 v[200:203], v[158:159], off offset:512 nt
	s_waitcnt vmcnt(20)
	v_pk_fma_f32 v[46:47], v[46:47], v[130:131], v[206:207]
	v_pk_fma_f32 v[44:45], v[44:45], v[128:129], v[204:205]
	global_store_dwordx4 v[156:157], v[44:47], off
	global_load_dwordx4 v[204:207], v[158:159], off offset:576 nt
	s_waitcnt vmcnt(20)
	v_pk_fma_f32 v[42:43], v[42:43], v[118:119], v[210:211]
	v_pk_fma_f32 v[40:41], v[40:41], v[116:117], v[208:209]
	global_store_dwordx4 v[156:157], v[40:43], off offset:64
	s_waitcnt vmcnt(19)
	v_pk_fma_f32 v[38:39], v[38:39], v[110:111], v[170:171]
	v_pk_fma_f32 v[36:37], v[36:37], v[108:109], v[168:169]
	global_store_dwordx4 v[156:157], v[36:39], off offset:512
	s_waitcnt vmcnt(18)
	v_pk_fma_f32 v[34:35], v[34:35], v[66:67], v[174:175]
	v_pk_fma_f32 v[32:33], v[32:33], v[64:65], v[172:173]
	global_store_dwordx4 v[156:157], v[32:35], off offset:576
	v_lshl_add_u64 v[156:157], v[156:157], 0, s[98:99]
	s_waitcnt vmcnt(17)
	v_pk_fma_f32 v[30:31], v[30:31], v[130:131], v[178:179]
	v_pk_fma_f32 v[28:29], v[28:29], v[128:129], v[176:177]
	global_store_dwordx4 v[156:157], v[28:31], off
	s_waitcnt vmcnt(16)
	v_pk_fma_f32 v[26:27], v[26:27], v[118:119], v[182:183]
	v_pk_fma_f32 v[24:25], v[24:25], v[116:117], v[180:181]
	global_store_dwordx4 v[156:157], v[24:27], off offset:64
	s_waitcnt vmcnt(15)
	v_pk_fma_f32 v[22:23], v[22:23], v[110:111], v[186:187]
	v_pk_fma_f32 v[20:21], v[20:21], v[108:109], v[184:185]
	global_store_dwordx4 v[156:157], v[20:23], off offset:512
	s_waitcnt vmcnt(14)
	v_pk_fma_f32 v[18:19], v[18:19], v[66:67], v[190:191]
	v_pk_fma_f32 v[16:17], v[16:17], v[64:65], v[188:189]
	global_store_dwordx4 v[156:157], v[16:19], off offset:576
	v_lshl_add_u64 v[156:157], v[156:157], 0, s[98:99]
	s_waitcnt vmcnt(13)
	v_pk_fma_f32 v[14:15], v[14:15], v[130:131], v[194:195]
	v_pk_fma_f32 v[12:13], v[12:13], v[128:129], v[192:193]
	global_store_dwordx4 v[156:157], v[12:15], off
	s_waitcnt vmcnt(12)
	v_pk_fma_f32 v[10:11], v[10:11], v[118:119], v[198:199]
	v_pk_fma_f32 v[8:9], v[8:9], v[116:117], v[196:197]
	global_store_dwordx4 v[156:157], v[8:11], off offset:64
	s_waitcnt vmcnt(11)
	v_pk_fma_f32 v[6:7], v[6:7], v[110:111], v[202:203]
	v_pk_fma_f32 v[4:5], v[4:5], v[108:109], v[200:201]
	global_store_dwordx4 v[156:157], v[4:7], off offset:512
	s_waitcnt vmcnt(10)
	v_pk_fma_f32 v[2:3], v[2:3], v[66:67], v[206:207]
	v_pk_fma_f32 v[0:1], v[0:1], v[64:65], v[204:205]
	global_store_dwordx4 v[156:157], v[0:3], off offset:576
	s_andn2_b64 vcc, exec, s[0:1]
	s_cbranch_vccnz .LBB0_1063
	s_andn2_b64 vcc, exec, s[2:3]
	s_cbranch_vccnz .LBB0_1062
	s_barrier
	s_branch .LBB0_1062

; __global__ void __launch_bounds__(NTHR, 2) fwd_megakernel(Args a) {
	.amdhsa_kernel _Z14fwd_megakernel4Args
		.amdhsa_group_segment_fixed_size 0
		.amdhsa_private_segment_fixed_size 0
		.amdhsa_kernarg_size 408
		.amdhsa_user_sgpr_count 2
		.amdhsa_user_sgpr_dispatch_ptr 0
		.amdhsa_user_sgpr_queue_ptr 0
		.amdhsa_user_sgpr_kernarg_segment_ptr 1
		.amdhsa_user_sgpr_dispatch_id 0
		.amdhsa_user_sgpr_kernarg_preload_length 0
		.amdhsa_user_sgpr_kernarg_preload_offset 0
		.amdhsa_user_sgpr_private_segment_size 0
		.amdhsa_uses_dynamic_stack 0
		.amdhsa_enable_private_segment 0
		.amdhsa_system_sgpr_workgroup_id_x 1
		.amdhsa_system_sgpr_workgroup_id_y 0
		.amdhsa_system_sgpr_workgroup_id_z 0
		.amdhsa_system_sgpr_workgroup_info 0
		.amdhsa_system_vgpr_workitem_id 2
		.amdhsa_next_free_vgpr 237
		.amdhsa_next_free_sgpr 102
		.amdhsa_accum_offset 240
		.amdhsa_reserve_vcc 1
		.amdhsa_float_round_mode_32 0
		.amdhsa_float_round_mode_16_64 0
		.amdhsa_float_denorm_mode_32 3
		.amdhsa_float_denorm_mode_16_64 3
		.amdhsa_dx10_clamp 1
		.amdhsa_ieee_mode 1
		.amdhsa_fp16_overflow 0
		.amdhsa_tg_split 0
		.amdhsa_exception_fp_ieee_invalid_op 0
		.amdhsa_exception_fp_denorm_src 0
		.amdhsa_exception_fp_ieee_div_zero 0
		.amdhsa_exception_fp_ieee_overflow 0
		.amdhsa_exception_fp_ieee_underflow 0
		.amdhsa_exception_fp_ieee_inexact 0
		.amdhsa_exception_int_div_zero 0
	.end_amdhsa_kernel

; __global__ void __launch_bounds__(NTHR, 2) fwd_megakernel(Args a) {
amdhsa.kernels:
  - .agpr_count:     0
    .args:
      - .offset:         0
        .size:           152
        .value_kind:     by_value
      - .offset:         152
        .size:           4
        .value_kind:     hidden_block_count_x
      - .offset:         156
        .size:           4
        .value_kind:     hidden_block_count_y
      - .offset:         160
        .size:           4
        .value_kind:     hidden_block_count_z
      - .offset:         164
        .size:           2
        .value_kind:     hidden_group_size_x
      - .offset:         166
        .size:           2
        .value_kind:     hidden_group_size_y
      - .offset:         168
        .size:           2
        .value_kind:     hidden_group_size_z
      - .offset:         170
        .size:           2
        .value_kind:     hidden_remainder_x
      - .offset:         172
        .size:           2
        .value_kind:     hidden_remainder_y
      - .offset:         174
        .size:           2
        .value_kind:     hidden_remainder_z
      - .offset:         192
        .size:           8
        .value_kind:     hidden_global_offset_x
      - .offset:         200
        .size:           8
        .value_kind:     hidden_global_offset_y
      - .offset:         208
        .size:           8
        .value_kind:     hidden_global_offset_z
      - .offset:         216
        .size:           2
        .value_kind:     hidden_grid_dims
      - .offset:         240
        .size:           8
        .value_kind:     hidden_multigrid_sync_arg
      - .offset:         272
        .size:           4
        .value_kind:     hidden_dynamic_lds_size
    .group_segment_fixed_size: 0
    .kernarg_segment_align: 8
    .kernarg_segment_size: 408
    .language:       OpenCL C
    .language_version:
      - 2
      - 0
    .max_flat_workgroup_size: 512
    .name:           _Z14fwd_megakernel4Args
    .private_segment_fixed_size: 0
    .sgpr_count:     108
    .sgpr_spill_count: 83
    .symbol:         _Z14fwd_megakernel4Args.kd
    .uniform_work_group_size: 1
    .uses_dynamic_stack: false
    .vgpr_count:     237
    .vgpr_spill_count: 0
    .wavefront_size: 64
